# prologue outputs (layer-0 weight prep, cache copies, first norm H2) stored write-through (sc1): no dirty L2 to flush at the first grid barrier
# speedup vs baseline: 1.0059x; 1.0001x over previous
.LBB0_1538:
	s_or_b64 exec, exec, s[2:3]
	ds_read2_b32 v[30:31], v22 offset1:8
	ds_read2_b32 v[32:33], v22 offset0:33 offset1:41
	ds_read2_b32 v[36:37], v22 offset0:66 offset1:74
	ds_read2_b32 v[38:39], v22 offset0:99 offset1:107
	ds_read2_b32 v[40:41], v22 offset0:132 offset1:140
	ds_read2_b32 v[42:43], v22 offset0:165 offset1:173
	ds_read2_b32 v[44:45], v22 offset0:198 offset1:206
	ds_read2_b32 v[46:47], v22 offset0:231 offset1:239
	v_lshlrev_b32_e32 v112, 1, v29
	v_lshl_add_u64 v[10:11], v[10:11], 0, v[112:113]
	v_mov_b32_e32 v9, v113
	v_lshl_add_u64 v[34:35], v[10:11], 0, v[8:9]
	s_waitcnt lgkmcnt(7)
	v_mov_b32_e32 v10, v30
	s_waitcnt lgkmcnt(6)
	v_mov_b32_e32 v11, v32
	s_waitcnt lgkmcnt(5)
	v_mov_b32_e32 v12, v36
	s_waitcnt lgkmcnt(4)
	v_mov_b32_e32 v13, v38
	s_waitcnt vmcnt(0)
	v_pk_mul_f32 v[10:11], v[14:15], v[10:11]
	v_pk_mul_f32 v[12:13], v[16:17], v[12:13]
	v_cvt_pk_bf16_f32 v10, v10, v11
	v_cvt_pk_bf16_f32 v11, v12, v13
	s_waitcnt lgkmcnt(3)
	v_mov_b32_e32 v12, v40
	s_waitcnt lgkmcnt(2)
	v_mov_b32_e32 v13, v42
	s_waitcnt lgkmcnt(1)
	v_mov_b32_e32 v48, v44
	s_waitcnt lgkmcnt(0)
	v_mov_b32_e32 v49, v46
	v_or_b32_e32 v7, v28, v5
	v_pk_mul_f32 v[12:13], v[18:19], v[12:13]
	v_pk_mul_f32 v[48:49], v[20:21], v[48:49]
	v_mul_u32_u24_e32 v112, v27, v7
	v_cvt_pk_bf16_f32 v12, v12, v13
	v_cvt_pk_bf16_f32 v13, v48, v49
	v_lshl_add_u64 v[48:49], v[112:113], 1, v[34:35]
	v_mov_b32_e32 v32, v31
	v_mov_b32_e32 v38, v37
	global_store_dwordx4 v[48:49], v[10:13], off sc1
	v_mov_b32_e32 v42, v41
	v_mov_b32_e32 v46, v45
	v_pk_mul_f32 v[10:11], v[14:15], v[32:33]
	v_pk_mul_f32 v[12:13], v[16:17], v[38:39]
	v_or_b32_e32 v7, v28, v23
	v_cvt_pk_bf16_f32 v10, v10, v11
	v_cvt_pk_bf16_f32 v11, v12, v13
	v_pk_mul_f32 v[12:13], v[18:19], v[42:43]
	v_pk_mul_f32 v[30:31], v[20:21], v[46:47]
	v_mul_u32_u24_e32 v112, v27, v7
	v_cvt_pk_bf16_f32 v12, v12, v13
	v_cvt_pk_bf16_f32 v13, v30, v31
	v_lshl_add_u64 v[36:37], v[112:113], 1, v[34:35]
	ds_read2_b32 v[30:31], v22 offset0:16 offset1:24
	ds_read2_b32 v[32:33], v22 offset0:49 offset1:57
	global_store_dwordx4 v[36:37], v[10:13], off sc1
	ds_read2_b32 v[36:37], v22 offset0:82 offset1:90
	ds_read2_b32 v[38:39], v22 offset0:115 offset1:123
	ds_read2_b32 v[40:41], v22 offset0:148 offset1:156
	ds_read2_b32 v[42:43], v22 offset0:181 offset1:189
	ds_read2_b32 v[44:45], v22 offset0:214 offset1:222
	ds_read2_b32 v[46:47], v22 offset0:247 offset1:255
	s_waitcnt lgkmcnt(7)
	v_mov_b32_e32 v10, v30
	s_waitcnt lgkmcnt(6)
	v_mov_b32_e32 v11, v32
	s_waitcnt lgkmcnt(5)
	v_mov_b32_e32 v12, v36
	s_waitcnt lgkmcnt(4)
	v_mov_b32_e32 v13, v38
	v_pk_mul_f32 v[10:11], v[14:15], v[10:11]
	v_pk_mul_f32 v[12:13], v[16:17], v[12:13]
	v_cvt_pk_bf16_f32 v10, v10, v11
	v_cvt_pk_bf16_f32 v11, v12, v13
	s_waitcnt lgkmcnt(3)
	v_mov_b32_e32 v12, v40
	s_waitcnt lgkmcnt(2)
	v_mov_b32_e32 v13, v42
	s_waitcnt lgkmcnt(1)
	v_mov_b32_e32 v48, v44
	s_waitcnt lgkmcnt(0)
	v_mov_b32_e32 v49, v46
	v_or_b32_e32 v7, v28, v24
	v_pk_mul_f32 v[12:13], v[18:19], v[12:13]
	v_pk_mul_f32 v[48:49], v[20:21], v[48:49]
	v_mul_u32_u24_e32 v112, v27, v7
	v_cvt_pk_bf16_f32 v12, v12, v13
	v_cvt_pk_bf16_f32 v13, v48, v49
	v_lshl_add_u64 v[48:49], v[112:113], 1, v[34:35]
	v_mov_b32_e32 v32, v31
	v_mov_b32_e32 v38, v37
	global_store_dwordx4 v[48:49], v[10:13], off sc1
	v_mov_b32_e32 v42, v41
	v_mov_b32_e32 v46, v45
	v_pk_mul_f32 v[10:11], v[14:15], v[32:33]
	v_pk_mul_f32 v[12:13], v[16:17], v[38:39]
	v_or_b32_e32 v7, v28, v25
	v_cvt_pk_bf16_f32 v10, v10, v11
	v_cvt_pk_bf16_f32 v11, v12, v13
	v_pk_mul_f32 v[12:13], v[18:19], v[42:43]
	v_pk_mul_f32 v[14:15], v[20:21], v[46:47]
	v_mul_u32_u24_e32 v112, v27, v7
	v_cvt_pk_bf16_f32 v12, v12, v13
	v_cvt_pk_bf16_f32 v13, v14, v15
	v_lshl_add_u64 v[14:15], v[112:113], 1, v[34:35]
	global_store_dwordx4 v[14:15], v[10:13], off sc1
	v_add_u32_e32 v3, s14, v3
	s_movk_i32 s2, 0x89f
	s_waitcnt lgkmcnt(0)
	v_cmp_lt_i32_e32 vcc, s2, v3
	s_or_b64 s[6:7], vcc, s[6:7]
	s_andn2_b64 exec, exec, s[6:7]
	s_cbranch_execz .LBB0_1620

.LBB0_1622:
	s_or_b64 exec, exec, s[10:11]
	global_load_dwordx4 v[16:19], v[4:5], off
	global_load_dwordx4 v[20:23], v[4:5], off offset:16
	v_and_b32_e32 v112, 0x1ff, v2
	v_lshl_add_u64 v[2:3], v[6:7], 0, v[112:113]
	s_waitcnt lgkmcnt(0)
	v_lshl_add_u64 v[4:5], s[4:5], 0, v[10:11]
	v_add_u32_e32 v14, s2, v14
	v_lshlrev_b64 v[2:3], v8, v[2:3]
	v_cmp_lt_i32_e32 vcc, s51, v14
	v_lshl_add_u64 v[2:3], v[4:5], 0, v[2:3]
	s_or_b64 s[8:9], vcc, s[8:9]
	v_lshl_add_u64 v[4:5], v[0:1], 1, v[2:3]
	v_add_u32_e32 v13, s3, v13
	s_waitcnt vmcnt(1)
	v_cvt_pk_bf16_f32 v0, v16, v17
	v_cvt_pk_bf16_f32 v1, v18, v19
	s_waitcnt vmcnt(0)
	v_cvt_pk_bf16_f32 v2, v20, v21
	v_cvt_pk_bf16_f32 v3, v22, v23
	global_store_dwordx4 v[4:5], v[0:3], off sc1
	s_andn2_b64 exec, exec, s[8:9]
	s_cbranch_execz .LBB0_1627

.LBB0_1644:
	s_or_b64 exec, exec, s[6:7]
	global_load_dwordx2 v[12:13], v[12:13], off
	s_waitcnt vmcnt(3)
	v_pk_mul_f32 v[14:15], v[30:31], v[30:31]
	v_pk_mul_f32 v[16:17], v[28:29], v[28:29]
	v_pk_mul_f32 v[18:19], v[26:27], v[26:27]
	v_pk_mul_f32 v[20:21], v[24:25], v[24:25]
	v_pk_mov_b32 v[50:51], v[16:17], v[14:15] op_sel:[1,0]
	v_mov_b32_e32 v17, v15
	v_pk_mov_b32 v[14:15], v[20:21], v[18:19] op_sel:[1,0]
	v_mov_b32_e32 v21, v19
	s_waitcnt vmcnt(1)
	v_mul_f32_e32 v22, v5, v5
	v_mul_f32_e32 v48, v7, v7
	v_pk_add_f32 v[16:17], v[50:51], v[16:17]
	v_pk_add_f32 v[14:15], v[14:15], v[20:21]
	v_mul_f32_e32 v9, v0, v0
	v_mul_f32_e32 v35, v1, v1
	v_mul_f32_e32 v43, v2, v2
	v_mul_f32_e32 v45, v3, v3
	v_pk_fma_f32 v[18:19], v[4:5], v[4:5], v[22:23] op_sel_hi:[1,1,0]
	v_pk_fma_f32 v[22:23], v[6:7], v[6:7], v[48:49] op_sel_hi:[1,1,0]
	v_pk_add_f32 v[16:17], v[16:17], v[16:17] op_sel:[0,1] op_sel_hi:[1,0]
	v_pk_add_f32 v[14:15], v[14:15], v[14:15] op_sel:[0,1] op_sel_hi:[1,0]
	v_mov_b32_e32 v19, v43
	v_mov_b32_e32 v23, v45
	v_mov_b32_e32 v17, v9
	v_mov_b32_e32 v15, v35
	v_pk_add_f32 v[18:19], v[18:19], v[22:23]
	v_pk_add_f32 v[14:15], v[16:17], v[14:15]
	v_ashrrev_i32_e32 v8, 10, v8
	v_pk_add_f32 v[14:15], v[14:15], v[18:19]
	v_add_u32_e32 v35, 1, v8
	v_add_f32_e32 v9, v14, v15
	ds_swizzle_b32 v14, v9 offset:swizzle(SWAP,1)
	v_lshlrev_b64 v[10:11], 12, v[10:11]
	v_cndmask_b32_e64 v8, v35, 0, s[4:5]
	v_mul_hi_i32_i24_e32 v57, 0x3000, v8
	v_mul_i32_i24_e32 v56, 0x3000, v8
	s_waitcnt lgkmcnt(0)
	v_add_f32_e32 v9, v9, v14
	ds_swizzle_b32 v14, v9 offset:swizzle(SWAP,2)
	s_mov_b64 s[2:3], s[0:1]
	v_mov_b32_e32 v43, v113
	s_mov_b64 s[20:21], 0x101000
	s_mov_b64 s[6:7], 0x100000
	s_waitcnt lgkmcnt(0)
	v_add_f32_e32 v9, v9, v14
	ds_swizzle_b32 v14, v9 offset:swizzle(SWAP,4)
	v_cndmask_b32_e64 v35, v35, 0, vcc
	v_lshlrev_b64 v[46:47], 11, v[46:47]
	v_lshl_add_u64 v[46:47], v[38:39], 0, v[46:47]
	v_lshl_add_u64 v[32:33], v[32:33], 0, s[10:11]
	s_waitcnt lgkmcnt(0)
	v_add_f32_e32 v9, v9, v14
	ds_swizzle_b32 v14, v9 offset:swizzle(SWAP,8)
	s_waitcnt lgkmcnt(0)
	v_add_f32_e32 v9, v9, v14
	ds_swizzle_b32 v14, v9 offset:swizzle(SWAP,16)
	s_waitcnt lgkmcnt(0)
	v_add_f32_e32 v45, v9, v14
	v_mov_b32_e32 v76, v45
	s_waitcnt vmcnt(0)
	v_lshl_add_u64 v[8:9], v[12:13], 0, v[10:11]
	v_lshl_add_u64 v[8:9], v[8:9], 0, v[112:113]
	global_load_dwordx4 v[16:19], v[8:9], off offset:16
	global_load_dwordx4 v[20:23], v[8:9], off
	global_load_dwordx4 v[12:15], v[8:9], off offset:2048
	s_nop 0
	global_load_dwordx4 v[8:11], v[8:9], off offset:2064
	s_load_dwordx2 s[2:3], s[2:3], 0xd0
	s_nop 1
	v_permlane32_swap_b32 v45, v76
	s_nop 1
	global_load_dwordx4 v[48:51], v[36:37], off offset:16
	global_load_dwordx4 v[52:55], v[36:37], off
	v_add_f32_e32 v45, v45, v76
	v_fmamk_f32 v45, v45, 0x3a800000, v242
	s_waitcnt lgkmcnt(0)
	v_lshl_add_u64 v[56:57], s[2:3], 0, v[56:57]
	v_lshl_add_u64 v[72:73], v[56:57], 0, s[20:21]
	v_lshl_add_u64 v[68:69], v[56:57], 0, v[42:43]
	v_lshl_add_u64 v[60:61], v[72:73], 0, v[42:43]
	v_add_co_u32_e64 v64, s[4:5], s54, v68
	global_load_dwordx4 v[56:59], v[60:61], off offset:16
	s_nop 0
	global_load_dwordx4 v[60:63], v[60:61], off
	v_addc_co_u32_e64 v65, s[4:5], 0, v69, s[4:5]
	v_lshl_add_u64 v[74:75], v[68:69], 0, s[6:7]
	global_load_dwordx4 v[64:67], v[64:65], off
	v_mul_f32_e32 v76, 0x4b800000, v45
	global_load_dwordx4 v[68:71], v[74:75], off offset:16
	v_cmp_gt_f32_e64 s[4:5], s72, v45
	s_mov_b64 s[2:3], s[0:1]
	s_waitcnt vmcnt(6)
	v_mul_f32_e32 v80, v10, v10
	v_cndmask_b32_e64 v45, v45, v76, s[4:5]
	v_rsq_f32_e32 v76, v45
	v_mov_b32_e32 v45, v113
	v_mul_f32_e32 v81, v11, v11
	v_mul_f32_e32 v77, 0x45800000, v76
	v_cndmask_b32_e64 v76, v76, v77, s[4:5]
	v_pk_mul_f32 v[30:31], v[30:31], v[76:77] op_sel_hi:[1,0]
	v_pk_mul_f32 v[28:29], v[28:29], v[76:77] op_sel_hi:[1,0]
	v_pk_mul_f32 v[26:27], v[26:27], v[76:77] op_sel_hi:[1,0]
	v_pk_mul_f32 v[24:25], v[24:25], v[76:77] op_sel_hi:[1,0]
	s_waitcnt vmcnt(4)
	v_pk_mul_f32 v[28:29], v[52:53], v[28:29]
	v_pk_mul_f32 v[30:31], v[54:55], v[30:31]
	v_pk_mul_f32 v[24:25], v[48:49], v[24:25]
	v_pk_mul_f32 v[26:27], v[50:51], v[26:27]
	s_waitcnt vmcnt(2)
	v_pk_add_f32 v[48:49], v[62:63], 1.0 op_sel_hi:[1,0]
	v_pk_add_f32 v[50:51], v[60:61], 1.0 op_sel_hi:[1,0]
	v_pk_add_f32 v[52:53], v[58:59], 1.0 op_sel_hi:[1,0]
	v_pk_add_f32 v[54:55], v[56:57], 1.0 op_sel_hi:[1,0]
	s_waitcnt vmcnt(1)
	v_pk_fma_f32 v[30:31], v[48:49], v[30:31], v[66:67]
	v_pk_fma_f32 v[28:29], v[50:51], v[28:29], v[64:65]
	s_waitcnt vmcnt(0)
	v_pk_fma_f32 v[48:49], v[52:53], v[26:27], v[70:71]
	v_pk_fma_f32 v[26:27], v[54:55], v[24:25], v[68:69]
	v_cvt_pk_bf16_f32 v24, v28, v29
	v_cvt_pk_bf16_f32 v25, v30, v31
	v_cvt_pk_bf16_f32 v26, v26, v27
	v_cvt_pk_bf16_f32 v27, v48, v49
	global_store_dwordx4 v[40:41], v[24:27], off sc1
	global_load_dwordx4 v[24:27], v[36:37], off offset:2048
	v_lshl_add_u64 v[52:53], v[72:73], 0, v[44:45]
	global_load_dwordx4 v[28:31], v[52:53], off
	global_load_dwordx4 v[48:51], v[36:37], off offset:2064
	s_nop 0
	global_load_dwordx4 v[52:55], v[52:53], off offset:16
	s_nop 0
	global_load_dwordx4 v[56:59], v[74:75], off offset:2048
	global_load_dwordx4 v[60:63], v[74:75], off offset:2064
	v_pk_mul_f32 v[64:65], v[22:23], v[22:23]
	v_pk_mul_f32 v[66:67], v[20:21], v[20:21]
	v_pk_mul_f32 v[68:69], v[18:19], v[18:19]
	v_pk_mul_f32 v[70:71], v[16:17], v[16:17]
	v_pk_mov_b32 v[78:79], v[66:67], v[64:65] op_sel:[1,0]
	v_mov_b32_e32 v67, v65
	v_pk_mov_b32 v[64:65], v[70:71], v[68:69] op_sel:[1,0]
	v_mov_b32_e32 v71, v69
	v_mul_f32_e32 v75, v8, v8
	v_mul_f32_e32 v72, v13, v13
	v_mul_f32_e32 v74, v15, v15
	v_pk_add_f32 v[66:67], v[78:79], v[66:67]
	v_pk_add_f32 v[64:65], v[64:65], v[70:71]
	v_mul_f32_e32 v77, v9, v9
	v_pk_fma_f32 v[68:69], v[12:13], v[12:13], v[72:73] op_sel_hi:[1,1,0]
	v_pk_fma_f32 v[72:73], v[14:15], v[14:15], v[74:75] op_sel_hi:[1,1,0]
	v_pk_add_f32 v[66:67], v[66:67], v[66:67] op_sel:[0,1] op_sel_hi:[1,0]
	v_pk_add_f32 v[64:65], v[64:65], v[64:65] op_sel:[0,1] op_sel_hi:[1,0]
	v_mov_b32_e32 v69, v80
	v_mov_b32_e32 v73, v81
	v_mov_b32_e32 v67, v75
	v_mov_b32_e32 v65, v77
	v_pk_add_f32 v[68:69], v[68:69], v[72:73]
	v_pk_add_f32 v[64:65], v[66:67], v[64:65]
	v_pk_mul_f32 v[6:7], v[6:7], v[76:77] op_sel_hi:[1,0]
	v_pk_add_f32 v[64:65], v[64:65], v[68:69]
	v_pk_mul_f32 v[4:5], v[4:5], v[76:77] op_sel_hi:[1,0]
	v_add_f32_e32 v64, v64, v65
	ds_swizzle_b32 v65, v64 offset:swizzle(SWAP,1)
	v_pk_mul_f32 v[2:3], v[2:3], v[76:77] op_sel_hi:[1,0]
	v_pk_mul_f32 v[0:1], v[0:1], v[76:77] op_sel_hi:[1,0]
	s_waitcnt lgkmcnt(0)
	v_add_f32_e32 v64, v64, v65
	ds_swizzle_b32 v65, v64 offset:swizzle(SWAP,2)
	s_waitcnt lgkmcnt(0)
	v_add_f32_e32 v64, v64, v65
	ds_swizzle_b32 v65, v64 offset:swizzle(SWAP,4)
	s_waitcnt lgkmcnt(0)
	v_add_f32_e32 v66, v64, v65
	ds_swizzle_b32 v67, v66 offset:swizzle(SWAP,8)
	v_mul_hi_i32_i24_e32 v65, 0x3000, v35
	v_mul_i32_i24_e32 v64, 0x3000, v35
	s_waitcnt lgkmcnt(0)
	v_add_f32_e32 v35, v66, v67
	ds_swizzle_b32 v66, v35 offset:swizzle(SWAP,16)
	s_waitcnt lgkmcnt(0)
	v_add_f32_e32 v35, v35, v66
	s_waitcnt vmcnt(3)
	v_pk_mul_f32 v[0:1], v[48:49], v[0:1]
	v_pk_mul_f32 v[4:5], v[24:25], v[4:5]
	v_pk_mul_f32 v[6:7], v[26:27], v[6:7]
	v_pk_add_f32 v[24:25], v[30:31], 1.0 op_sel_hi:[1,0]
	v_pk_add_f32 v[26:27], v[28:29], 1.0 op_sel_hi:[1,0]
	v_pk_mul_f32 v[2:3], v[50:51], v[2:3]
	s_waitcnt vmcnt(2)
	v_pk_add_f32 v[28:29], v[54:55], 1.0 op_sel_hi:[1,0]
	v_pk_add_f32 v[30:31], v[52:53], 1.0 op_sel_hi:[1,0]
	s_waitcnt vmcnt(1)
	v_pk_fma_f32 v[6:7], v[24:25], v[6:7], v[58:59]
	v_pk_fma_f32 v[4:5], v[26:27], v[4:5], v[56:57]
	s_waitcnt vmcnt(0)
	v_pk_fma_f32 v[24:25], v[2:3], v[28:29], v[62:63]
	v_pk_fma_f32 v[2:3], v[0:1], v[30:31], v[60:61]
	v_cvt_pk_bf16_f32 v0, v4, v5
	v_cvt_pk_bf16_f32 v1, v6, v7
	v_cvt_pk_bf16_f32 v2, v2, v3
	v_cvt_pk_bf16_f32 v3, v24, v25
	global_store_dwordx4 v[40:41], v[0:3], off offset:1024 sc1
	s_load_dwordx2 s[2:3], s[2:3], 0xd0
	v_mov_b32_e32 v60, v35
	s_nop 1
	v_permlane32_swap_b32 v35, v60
	s_nop 1
	global_load_dwordx4 v[0:3], v[36:37], off offset:16
	global_load_dwordx4 v[4:7], v[36:37], off
	v_add_f32_e32 v35, v35, v60
	s_waitcnt lgkmcnt(0)
	v_lshl_add_u64 v[24:25], s[2:3], 0, v[64:65]
	v_lshl_add_u64 v[56:57], v[24:25], 0, s[20:21]
	v_lshl_add_u64 v[52:53], v[24:25], 0, v[42:43]
	v_lshl_add_u64 v[28:29], v[56:57], 0, v[42:43]
	v_add_co_u32_e32 v48, vcc, s54, v52
	global_load_dwordx4 v[24:27], v[28:29], off offset:16
	s_nop 0
	global_load_dwordx4 v[28:31], v[28:29], off
	v_addc_co_u32_e32 v49, vcc, 0, v53, vcc
	v_lshl_add_u64 v[58:59], v[52:53], 0, s[6:7]
	global_load_dwordx4 v[48:51], v[48:49], off
	v_fmamk_f32 v35, v35, 0x3a800000, v242
	global_load_dwordx4 v[52:55], v[58:59], off offset:16
	v_mul_f32_e32 v43, 0x4b800000, v35
	v_cmp_gt_f32_e32 vcc, s72, v35
	s_movk_i32 s2, 0x2fff
	v_lshl_add_u64 v[40:41], v[40:41], 0, s[12:13]
	v_cndmask_b32_e32 v35, v35, v43, vcc
	v_rsq_f32_e32 v35, v35
	s_nop 0
	v_mul_f32_e32 v43, 0x45800000, v35
	v_cndmask_b32_e32 v60, v35, v43, vcc
	v_pk_mul_f32 v[22:23], v[22:23], v[60:61] op_sel_hi:[1,0]
	v_pk_mul_f32 v[20:21], v[20:21], v[60:61] op_sel_hi:[1,0]
	v_pk_mul_f32 v[18:19], v[18:19], v[60:61] op_sel_hi:[1,0]
	v_pk_mul_f32 v[16:17], v[16:17], v[60:61] op_sel_hi:[1,0]
	v_pk_mul_f32 v[14:15], v[14:15], v[60:61] op_sel_hi:[1,0]
	v_pk_mul_f32 v[12:13], v[12:13], v[60:61] op_sel_hi:[1,0]
	v_pk_mul_f32 v[10:11], v[10:11], v[60:61] op_sel_hi:[1,0]
	v_pk_mul_f32 v[8:9], v[8:9], v[60:61] op_sel_hi:[1,0]
	v_cmp_lt_i32_e32 vcc, s2, v32
	s_or_b64 s[16:17], vcc, s[16:17]
	s_waitcnt vmcnt(5)
	v_pk_mul_f32 v[0:1], v[0:1], v[16:17]
	s_waitcnt vmcnt(4)
	v_pk_mul_f32 v[4:5], v[4:5], v[20:21]
	v_pk_mul_f32 v[6:7], v[6:7], v[22:23]
	v_pk_mul_f32 v[2:3], v[2:3], v[18:19]
	s_waitcnt vmcnt(3)
	v_pk_add_f32 v[20:21], v[26:27], 1.0 op_sel_hi:[1,0]
	s_waitcnt vmcnt(2)
	v_pk_add_f32 v[16:17], v[30:31], 1.0 op_sel_hi:[1,0]
	v_pk_add_f32 v[18:19], v[28:29], 1.0 op_sel_hi:[1,0]
	v_pk_add_f32 v[22:23], v[24:25], 1.0 op_sel_hi:[1,0]
	s_waitcnt vmcnt(1)
	v_pk_fma_f32 v[6:7], v[16:17], v[6:7], v[50:51]
	v_pk_fma_f32 v[4:5], v[18:19], v[4:5], v[48:49]
	s_waitcnt vmcnt(0)
	v_pk_fma_f32 v[16:17], v[20:21], v[2:3], v[54:55]
	v_pk_fma_f32 v[2:3], v[22:23], v[0:1], v[52:53]
	v_cvt_pk_bf16_f32 v0, v4, v5
	v_cvt_pk_bf16_f32 v1, v6, v7
	v_cvt_pk_bf16_f32 v2, v2, v3
	v_cvt_pk_bf16_f32 v3, v16, v17
	global_store_dwordx4 v[46:47], v[0:3], off sc1
	global_load_dwordx4 v[0:3], v[36:37], off offset:2048
	v_lshl_add_u64 v[20:21], v[56:57], 0, v[44:45]
	global_load_dwordx4 v[4:7], v[20:21], off
	global_load_dwordx4 v[16:19], v[36:37], off offset:2064
	s_nop 0
	global_load_dwordx4 v[20:23], v[20:21], off offset:16
	s_nop 0
	global_load_dwordx4 v[24:27], v[58:59], off offset:2048
	global_load_dwordx4 v[28:31], v[58:59], off offset:2064
	s_waitcnt vmcnt(4)
	v_pk_add_f32 v[6:7], v[6:7], 1.0 op_sel_hi:[1,0]
	v_pk_add_f32 v[4:5], v[4:5], 1.0 op_sel_hi:[1,0]
	v_pk_mul_f32 v[0:1], v[0:1], v[12:13]
	v_pk_mul_f32 v[2:3], v[2:3], v[14:15]
	s_waitcnt vmcnt(3)
	v_pk_mul_f32 v[8:9], v[16:17], v[8:9]
	v_pk_mul_f32 v[10:11], v[18:19], v[10:11]
	s_waitcnt vmcnt(2)
	v_pk_add_f32 v[12:13], v[22:23], 1.0 op_sel_hi:[1,0]
	v_pk_add_f32 v[14:15], v[20:21], 1.0 op_sel_hi:[1,0]
	s_waitcnt vmcnt(1)
	v_pk_fma_f32 v[2:3], v[6:7], v[2:3], v[26:27]
	v_pk_fma_f32 v[0:1], v[4:5], v[0:1], v[24:25]
	s_waitcnt vmcnt(0)
	v_pk_fma_f32 v[4:5], v[10:11], v[12:13], v[30:31]
	v_pk_fma_f32 v[6:7], v[8:9], v[14:15], v[28:29]
	v_cvt_pk_bf16_f32 v0, v0, v1
	v_cvt_pk_bf16_f32 v1, v2, v3
	v_cvt_pk_bf16_f32 v2, v6, v7
	v_cvt_pk_bf16_f32 v3, v4, v5
	global_store_dwordx4 v[46:47], v[0:3], off offset:1024 sc1
	s_andn2_b64 exec, exec, s[16:17]
	s_cbranch_execz .LBB0_8
